# v84 plus hand-written 256x128 16x16x32 tile on the 256-workgroup path of OUT0 (fp32 residual from the inputs as 16-byte loads, 16-byte fp16 stores)
# speedup vs baseline: 1.0668x; 1.0062x over previous
.LBB0_1270:
	s_and_b32 s50, s36, 56
	s_or_b32 s50, s50, s83
	s_lshl_b32 s50, s50, 8
	s_and_b32 s37, s36, 7
	s_lshl_b32 s37, s37, 7
	s_lshl_b32 s55, s50, 11
	s_add_u32 s28, s48, s55
	s_addc_u32 s29, s49, 0
	s_lshl_b32 s55, s37, 11
	s_add_u32 s30, s46, s55
	s_addc_u32 s31, s47, 0
	v_readfirstlane_b32 s55, v200
	s_lshr_b32 s55, s55, 6
	s_lshl_b32 s32, s55, 11
	s_add_u32 s32, s32, 16
	s_lshl_b32 s51, s55, 10
	s_add_u32 s51, s51, 0x4010
	s_lshl_b32 s55, s55, 15
	s_add_u32 s30, s30, s55
	s_addc_u32 s31, s31, 0
	s_lshl_b32 s55, s55, 1
	s_add_u32 s28, s28, s55
	s_addc_u32 s29, s29, 0
	v_bfe_u32 v173, v200, 4, 2
	v_sub_u32_e32 v173, 0, v173
	v_and_b32_e32 v173, 3, v173
	v_and_b32_e32 v172, 3, v200
	v_xor_b32_e32 v172, v172, v173
	v_bfe_u32 v173, v200, 2, 4
	v_lshlrev_b32_e32 v173, 11, v173
	v_lshl_or_b32 v170, v172, 4, v173
	v_add_u32_e32 v171, 0x8000, v170
	v_bfe_u32 v172, v200, 2, 2
	v_sub_u32_e32 v172, 0, v172
	v_and_b32_e32 v172, 3, v172
	v_bfe_u32 v173, v200, 4, 2
	v_xor_b32_e32 v172, v172, v173
	v_and_b32_e32 v173, 15, v200
	v_bfe_u32 v174, v200, 7, 2
	v_lshl_or_b32 v174, v174, 6, v173
	v_lshlrev_b32_e32 v174, 6, v174
	v_lshl_or_b32 v164, v172, 4, v174
	v_bfe_u32 v174, v200, 6, 1
	v_lshl_or_b32 v174, v174, 6, v173
	v_lshlrev_b32_e32 v174, 6, v174
	v_lshl_or_b32 v165, v172, 4, v174
	v_add_u32_e32 v165, 0x4000, v165
	v_bfe_u32 v172, v200, 6, 1
	v_bfe_u32 v173, v200, 4, 2
	v_lshlrev_b32_e32 v172, 6, v172
	v_lshl_or_b32 v172, v173, 2, v172
	v_add_u32_e32 v172, s37, v172
	v_lshlrev_b32_e32 v172, 2, v172
	global_load_dwordx4 v[132:135], v172, s[24:25]
	global_load_dwordx4 v[136:139], v172, s[24:25] offset:64
	global_load_dwordx4 v[140:143], v172, s[24:25] offset:128
	global_load_dwordx4 v[144:147], v172, s[24:25] offset:192
	s_mov_b32 s53, 0x0
	s_add_u32 m0, s32, s53
	s_nop 0
	global_load_lds_dwordx4 v170, s[28:29]
	s_add_u32 m0, s32, s53
	s_add_u32 m0, m0, 0x400
	s_nop 0
	global_load_lds_dwordx4 v171, s[28:29]
	s_add_u32 m0, s51, s53
	s_nop 0
	global_load_lds_dwordx4 v170, s[30:31]
	s_add_u32 s28, s28, 64
	s_addc_u32 s29, s29, 0
	s_add_u32 s30, s30, 64
	s_addc_u32 s31, s31, 0
	s_mov_b32 s53, 0x6000
	s_add_u32 m0, s32, s53
	s_nop 0
	global_load_lds_dwordx4 v170, s[28:29]
	s_add_u32 m0, s32, s53
	s_add_u32 m0, m0, 0x400
	s_nop 0
	global_load_lds_dwordx4 v171, s[28:29]
	s_add_u32 m0, s51, s53
	s_nop 0
	global_load_lds_dwordx4 v170, s[30:31]
	s_add_u32 s28, s28, 64
	s_addc_u32 s29, s29, 0
	s_add_u32 s30, s30, 64
	s_addc_u32 s31, s31, 0
	s_mov_b32 s53, 0xc000
	s_add_u32 m0, s32, s53
	s_nop 0
	global_load_lds_dwordx4 v170, s[28:29]
	s_add_u32 m0, s32, s53
	s_add_u32 m0, m0, 0x400
	s_nop 0
	global_load_lds_dwordx4 v171, s[28:29]
	s_add_u32 m0, s51, s53
	s_nop 0
	global_load_lds_dwordx4 v170, s[30:31]
	s_add_u32 s28, s28, 64
	s_addc_u32 s29, s29, 0
	s_add_u32 s30, s30, 64
	s_addc_u32 s31, s31, 0
	s_mov_b32 s53, 0x12000
	s_add_u32 m0, s32, s53
	s_nop 0
	global_load_lds_dwordx4 v170, s[28:29]
	s_add_u32 m0, s32, s53
	s_add_u32 m0, m0, 0x400
	s_nop 0
	global_load_lds_dwordx4 v171, s[28:29]
	s_add_u32 m0, s51, s53
	s_nop 0
	global_load_lds_dwordx4 v170, s[30:31]
	s_add_u32 s28, s28, 64
	s_addc_u32 s29, s29, 0
	s_add_u32 s30, s30, 64
	s_addc_u32 s31, s31, 0
	s_waitcnt vmcnt(12)
	v_mov_b32_e32 v4, v132
	v_mov_b32_e32 v5, v133
	v_mov_b32_e32 v6, v134
	v_mov_b32_e32 v7, v135
	v_mov_b32_e32 v8, v136
	v_mov_b32_e32 v9, v137
	v_mov_b32_e32 v10, v138
	v_mov_b32_e32 v11, v139
	v_mov_b32_e32 v12, v140
	v_mov_b32_e32 v13, v141
	v_mov_b32_e32 v14, v142
	v_mov_b32_e32 v15, v143
	v_mov_b32_e32 v16, v144
	v_mov_b32_e32 v17, v145
	v_mov_b32_e32 v18, v146
	v_mov_b32_e32 v19, v147
	v_mov_b32_e32 v20, v132
	v_mov_b32_e32 v21, v133
	v_mov_b32_e32 v22, v134
	v_mov_b32_e32 v23, v135
	v_mov_b32_e32 v24, v136
	v_mov_b32_e32 v25, v137
	v_mov_b32_e32 v26, v138
	v_mov_b32_e32 v27, v139
	v_mov_b32_e32 v28, v140
	v_mov_b32_e32 v29, v141
	v_mov_b32_e32 v30, v142
	v_mov_b32_e32 v31, v143
	v_mov_b32_e32 v32, v144
	v_mov_b32_e32 v33, v145
	v_mov_b32_e32 v34, v146
	v_mov_b32_e32 v35, v147
	v_mov_b32_e32 v36, v132
	v_mov_b32_e32 v37, v133
	v_mov_b32_e32 v38, v134
	v_mov_b32_e32 v39, v135
	v_mov_b32_e32 v40, v136
	v_mov_b32_e32 v41, v137
	v_mov_b32_e32 v42, v138
	v_mov_b32_e32 v43, v139
	v_mov_b32_e32 v44, v140
	v_mov_b32_e32 v45, v141
	v_mov_b32_e32 v46, v142
	v_mov_b32_e32 v47, v143
	v_mov_b32_e32 v48, v144
	v_mov_b32_e32 v49, v145
	v_mov_b32_e32 v50, v146
	v_mov_b32_e32 v51, v147
	v_mov_b32_e32 v52, v132
	v_mov_b32_e32 v53, v133
	v_mov_b32_e32 v54, v134
	v_mov_b32_e32 v55, v135
	v_mov_b32_e32 v56, v136
	v_mov_b32_e32 v57, v137
	v_mov_b32_e32 v58, v138
	v_mov_b32_e32 v59, v139
	v_mov_b32_e32 v60, v140
	v_mov_b32_e32 v61, v141
	v_mov_b32_e32 v62, v142
	v_mov_b32_e32 v63, v143
	v_mov_b32_e32 v64, v144
	v_mov_b32_e32 v65, v145
	v_mov_b32_e32 v66, v146
	v_mov_b32_e32 v67, v147
	s_waitcnt vmcnt(9)
	s_barrier
	s_mov_b32 s52, 0
	s_mov_b32 s54, 0
	s_nop 1
	v_add_u32_e32 v168, s52, v165
	v_add_u32_e32 v169, s52, v164
	ds_read_b128 v[132:135], v168 offset:16
	ds_read_b128 v[136:139], v168 offset:1040
	ds_read_b128 v[140:143], v168 offset:2064
	ds_read_b128 v[144:147], v168 offset:3088
	ds_read_b128 v[184:187], v169 offset:16
	ds_read_b128 v[188:191], v169 offset:1040
	s_waitcnt lgkmcnt(0)
.Lt_out0v:
	v_add_u32_e32 v169, s52, v164
	v_mfma_f32_16x16x32_f16 v[4:7], v[132:135], v[184:187], v[4:7]
	ds_read_b128 v[192:195], v169 offset:2064
	v_mfma_f32_16x16x32_f16 v[8:11], v[136:139], v[184:187], v[8:11]
	ds_read_b128 v[196:199], v169 offset:3088
	v_mfma_f32_16x16x32_f16 v[12:15], v[140:143], v[184:187], v[12:15]
	v_mfma_f32_16x16x32_f16 v[16:19], v[144:147], v[184:187], v[16:19]
	v_mfma_f32_16x16x32_f16 v[20:23], v[132:135], v[188:191], v[20:23]
	v_mfma_f32_16x16x32_f16 v[24:27], v[136:139], v[188:191], v[24:27]
	v_mfma_f32_16x16x32_f16 v[28:31], v[140:143], v[188:191], v[28:31]
	v_mfma_f32_16x16x32_f16 v[32:35], v[144:147], v[188:191], v[32:35]
	s_waitcnt vmcnt(6) lgkmcnt(0)
	s_barrier
	s_add_i32 s53, s52, 0x6000
	s_cmp_lg_u32 s52, 0x12000
	s_cselect_b32 s53, s53, 0
	v_add_u32_e32 v168, s53, v165
	v_add_u32_e32 v169, s53, v164
	v_mfma_f32_16x16x32_f16 v[36:39], v[132:135], v[192:195], v[36:39]
	ds_read_b128 v[148:151], v168 offset:16
	ds_read_b128 v[184:187], v169 offset:16
	v_mfma_f32_16x16x32_f16 v[40:43], v[136:139], v[192:195], v[40:43]
	ds_read_b128 v[152:155], v168 offset:1040
	ds_read_b128 v[188:191], v169 offset:1040
	v_mfma_f32_16x16x32_f16 v[44:47], v[140:143], v[192:195], v[44:47]
	ds_read_b128 v[156:159], v168 offset:2064
	v_mfma_f32_16x16x32_f16 v[48:51], v[144:147], v[192:195], v[48:51]
	ds_read_b128 v[160:163], v168 offset:3088
	v_mfma_f32_16x16x32_f16 v[52:55], v[132:135], v[196:199], v[52:55]
	s_add_u32 m0, s32, s52
	s_nop 0
	global_load_lds_dwordx4 v170, s[28:29]
	v_mfma_f32_16x16x32_f16 v[56:59], v[136:139], v[196:199], v[56:59]
	s_add_u32 m0, s32, s52
	s_add_u32 m0, m0, 0x400
	s_nop 0
	global_load_lds_dwordx4 v171, s[28:29]
	v_mfma_f32_16x16x32_f16 v[60:63], v[140:143], v[196:199], v[60:63]
	s_add_u32 m0, s51, s52
	s_nop 0
	global_load_lds_dwordx4 v170, s[30:31]
	v_mfma_f32_16x16x32_f16 v[64:67], v[144:147], v[196:199], v[64:67]
	s_waitcnt lgkmcnt(0)
	s_mov_b32 s52, s53
	s_add_u32 s28, s28, 64
	s_addc_u32 s29, s29, 0
	s_add_u32 s30, s30, 64
	s_addc_u32 s31, s31, 0
	v_add_u32_e32 v169, s52, v164
	v_mfma_f32_16x16x32_f16 v[4:7], v[148:151], v[184:187], v[4:7]
	ds_read_b128 v[192:195], v169 offset:2064
	v_mfma_f32_16x16x32_f16 v[8:11], v[152:155], v[184:187], v[8:11]
	ds_read_b128 v[196:199], v169 offset:3088
	v_mfma_f32_16x16x32_f16 v[12:15], v[156:159], v[184:187], v[12:15]
	v_mfma_f32_16x16x32_f16 v[16:19], v[160:163], v[184:187], v[16:19]
	v_mfma_f32_16x16x32_f16 v[20:23], v[148:151], v[188:191], v[20:23]
	v_mfma_f32_16x16x32_f16 v[24:27], v[152:155], v[188:191], v[24:27]
	v_mfma_f32_16x16x32_f16 v[28:31], v[156:159], v[188:191], v[28:31]
	v_mfma_f32_16x16x32_f16 v[32:35], v[160:163], v[188:191], v[32:35]
	s_waitcnt vmcnt(6) lgkmcnt(0)
	s_barrier
	s_add_i32 s53, s52, 0x6000
	s_cmp_lg_u32 s52, 0x12000
	s_cselect_b32 s53, s53, 0
	v_add_u32_e32 v168, s53, v165
	v_add_u32_e32 v169, s53, v164
	v_mfma_f32_16x16x32_f16 v[36:39], v[148:151], v[192:195], v[36:39]
	ds_read_b128 v[132:135], v168 offset:16
	ds_read_b128 v[184:187], v169 offset:16
	v_mfma_f32_16x16x32_f16 v[40:43], v[152:155], v[192:195], v[40:43]
	ds_read_b128 v[136:139], v168 offset:1040
	ds_read_b128 v[188:191], v169 offset:1040
	v_mfma_f32_16x16x32_f16 v[44:47], v[156:159], v[192:195], v[44:47]
	ds_read_b128 v[140:143], v168 offset:2064
	v_mfma_f32_16x16x32_f16 v[48:51], v[160:163], v[192:195], v[48:51]
	ds_read_b128 v[144:147], v168 offset:3088
	v_mfma_f32_16x16x32_f16 v[52:55], v[148:151], v[196:199], v[52:55]
	s_add_u32 m0, s32, s52
	s_nop 0
	global_load_lds_dwordx4 v170, s[28:29]
	v_mfma_f32_16x16x32_f16 v[56:59], v[152:155], v[196:199], v[56:59]
	s_add_u32 m0, s32, s52
	s_add_u32 m0, m0, 0x400
	s_nop 0
	global_load_lds_dwordx4 v171, s[28:29]
	v_mfma_f32_16x16x32_f16 v[60:63], v[156:159], v[196:199], v[60:63]
	s_add_u32 m0, s51, s52
	s_nop 0
	global_load_lds_dwordx4 v170, s[30:31]
	v_mfma_f32_16x16x32_f16 v[64:67], v[160:163], v[196:199], v[64:67]
	s_waitcnt lgkmcnt(0)
	s_mov_b32 s52, s53
	s_add_u32 s28, s28, 64
	s_addc_u32 s29, s29, 0
	s_add_u32 s30, s30, 64
	s_addc_u32 s31, s31, 0
	s_add_i32 s54, s54, 2
	s_cmp_lt_u32 s54, 28
	s_cbranch_scc1 .Lt_out0v
	v_add_u32_e32 v169, s52, v164
	v_mfma_f32_16x16x32_f16 v[4:7], v[132:135], v[184:187], v[4:7]
	ds_read_b128 v[192:195], v169 offset:2064
	v_mfma_f32_16x16x32_f16 v[8:11], v[136:139], v[184:187], v[8:11]
	ds_read_b128 v[196:199], v169 offset:3088
	v_mfma_f32_16x16x32_f16 v[12:15], v[140:143], v[184:187], v[12:15]
	v_mfma_f32_16x16x32_f16 v[16:19], v[144:147], v[184:187], v[16:19]
	v_mfma_f32_16x16x32_f16 v[20:23], v[132:135], v[188:191], v[20:23]
	v_mfma_f32_16x16x32_f16 v[24:27], v[136:139], v[188:191], v[24:27]
	v_mfma_f32_16x16x32_f16 v[28:31], v[140:143], v[188:191], v[28:31]
	v_mfma_f32_16x16x32_f16 v[32:35], v[144:147], v[188:191], v[32:35]
	s_waitcnt vmcnt(6) lgkmcnt(0)
	s_barrier
	s_add_i32 s53, s52, 0x6000
	s_cmp_lg_u32 s52, 0x12000
	s_cselect_b32 s53, s53, 0
	v_add_u32_e32 v168, s53, v165
	v_add_u32_e32 v169, s53, v164
	v_mfma_f32_16x16x32_f16 v[36:39], v[132:135], v[192:195], v[36:39]
	ds_read_b128 v[148:151], v168 offset:16
	ds_read_b128 v[184:187], v169 offset:16
	v_mfma_f32_16x16x32_f16 v[40:43], v[136:139], v[192:195], v[40:43]
	ds_read_b128 v[152:155], v168 offset:1040
	ds_read_b128 v[188:191], v169 offset:1040
	v_mfma_f32_16x16x32_f16 v[44:47], v[140:143], v[192:195], v[44:47]
	ds_read_b128 v[156:159], v168 offset:2064
	v_mfma_f32_16x16x32_f16 v[48:51], v[144:147], v[192:195], v[48:51]
	ds_read_b128 v[160:163], v168 offset:3088
	v_mfma_f32_16x16x32_f16 v[52:55], v[132:135], v[196:199], v[52:55]
	v_mfma_f32_16x16x32_f16 v[56:59], v[136:139], v[196:199], v[56:59]
	v_mfma_f32_16x16x32_f16 v[60:63], v[140:143], v[196:199], v[60:63]
	v_mfma_f32_16x16x32_f16 v[64:67], v[144:147], v[196:199], v[64:67]
	s_waitcnt lgkmcnt(0)
	s_mov_b32 s52, s53
	v_add_u32_e32 v169, s52, v164
	v_mfma_f32_16x16x32_f16 v[4:7], v[148:151], v[184:187], v[4:7]
	ds_read_b128 v[192:195], v169 offset:2064
	v_mfma_f32_16x16x32_f16 v[8:11], v[152:155], v[184:187], v[8:11]
	ds_read_b128 v[196:199], v169 offset:3088
	v_mfma_f32_16x16x32_f16 v[12:15], v[156:159], v[184:187], v[12:15]
	v_mfma_f32_16x16x32_f16 v[16:19], v[160:163], v[184:187], v[16:19]
	v_mfma_f32_16x16x32_f16 v[20:23], v[148:151], v[188:191], v[20:23]
	v_mfma_f32_16x16x32_f16 v[24:27], v[152:155], v[188:191], v[24:27]
	v_mfma_f32_16x16x32_f16 v[28:31], v[156:159], v[188:191], v[28:31]
	v_mfma_f32_16x16x32_f16 v[32:35], v[160:163], v[188:191], v[32:35]
	s_waitcnt vmcnt(3) lgkmcnt(0)
	s_barrier
	s_add_i32 s53, s52, 0x6000
	s_cmp_lg_u32 s52, 0x12000
	s_cselect_b32 s53, s53, 0
	v_add_u32_e32 v168, s53, v165
	v_add_u32_e32 v169, s53, v164
	v_mfma_f32_16x16x32_f16 v[36:39], v[148:151], v[192:195], v[36:39]
	ds_read_b128 v[132:135], v168 offset:16
	ds_read_b128 v[184:187], v169 offset:16
	v_mfma_f32_16x16x32_f16 v[40:43], v[152:155], v[192:195], v[40:43]
	ds_read_b128 v[136:139], v168 offset:1040
	ds_read_b128 v[188:191], v169 offset:1040
	v_mfma_f32_16x16x32_f16 v[44:47], v[156:159], v[192:195], v[44:47]
	ds_read_b128 v[140:143], v168 offset:2064
	v_mfma_f32_16x16x32_f16 v[48:51], v[160:163], v[192:195], v[48:51]
	ds_read_b128 v[144:147], v168 offset:3088
	v_mfma_f32_16x16x32_f16 v[52:55], v[148:151], v[196:199], v[52:55]
	v_mfma_f32_16x16x32_f16 v[56:59], v[152:155], v[196:199], v[56:59]
	v_mfma_f32_16x16x32_f16 v[60:63], v[156:159], v[196:199], v[60:63]
	v_mfma_f32_16x16x32_f16 v[64:67], v[160:163], v[196:199], v[64:67]
	s_waitcnt lgkmcnt(0)
	s_mov_b32 s52, s53
	v_add_u32_e32 v169, s52, v164
	v_mfma_f32_16x16x32_f16 v[4:7], v[132:135], v[184:187], v[4:7]
	ds_read_b128 v[192:195], v169 offset:2064
	v_mfma_f32_16x16x32_f16 v[8:11], v[136:139], v[184:187], v[8:11]
	ds_read_b128 v[196:199], v169 offset:3088
	v_mfma_f32_16x16x32_f16 v[12:15], v[140:143], v[184:187], v[12:15]
	v_mfma_f32_16x16x32_f16 v[16:19], v[144:147], v[184:187], v[16:19]
	v_mfma_f32_16x16x32_f16 v[20:23], v[132:135], v[188:191], v[20:23]
	v_mfma_f32_16x16x32_f16 v[24:27], v[136:139], v[188:191], v[24:27]
	v_mfma_f32_16x16x32_f16 v[28:31], v[140:143], v[188:191], v[28:31]
	v_mfma_f32_16x16x32_f16 v[32:35], v[144:147], v[188:191], v[32:35]
	s_waitcnt vmcnt(0) lgkmcnt(0)
	s_barrier
	s_add_i32 s53, s52, 0x6000
	s_cmp_lg_u32 s52, 0x12000
	s_cselect_b32 s53, s53, 0
	v_add_u32_e32 v168, s53, v165
	v_add_u32_e32 v169, s53, v164
	v_mfma_f32_16x16x32_f16 v[36:39], v[132:135], v[192:195], v[36:39]
	ds_read_b128 v[148:151], v168 offset:16
	ds_read_b128 v[184:187], v169 offset:16
	v_mfma_f32_16x16x32_f16 v[40:43], v[136:139], v[192:195], v[40:43]
	ds_read_b128 v[152:155], v168 offset:1040
	ds_read_b128 v[188:191], v169 offset:1040
	v_mfma_f32_16x16x32_f16 v[44:47], v[140:143], v[192:195], v[44:47]
	ds_read_b128 v[156:159], v168 offset:2064
	v_mfma_f32_16x16x32_f16 v[48:51], v[144:147], v[192:195], v[48:51]
	ds_read_b128 v[160:163], v168 offset:3088
	v_mfma_f32_16x16x32_f16 v[52:55], v[132:135], v[196:199], v[52:55]
	v_mfma_f32_16x16x32_f16 v[56:59], v[136:139], v[196:199], v[56:59]
	v_mfma_f32_16x16x32_f16 v[60:63], v[140:143], v[196:199], v[60:63]
	v_mfma_f32_16x16x32_f16 v[64:67], v[144:147], v[196:199], v[64:67]
	s_waitcnt lgkmcnt(0)
	s_mov_b32 s52, s53
	v_add_u32_e32 v169, s52, v164
	v_mfma_f32_16x16x32_f16 v[4:7], v[148:151], v[184:187], v[4:7]
	ds_read_b128 v[192:195], v169 offset:2064
	v_mfma_f32_16x16x32_f16 v[8:11], v[152:155], v[184:187], v[8:11]
	ds_read_b128 v[196:199], v169 offset:3088
	v_mfma_f32_16x16x32_f16 v[12:15], v[156:159], v[184:187], v[12:15]
	v_mfma_f32_16x16x32_f16 v[16:19], v[160:163], v[184:187], v[16:19]
	v_mfma_f32_16x16x32_f16 v[20:23], v[148:151], v[188:191], v[20:23]
	v_mfma_f32_16x16x32_f16 v[24:27], v[152:155], v[188:191], v[24:27]
	v_mfma_f32_16x16x32_f16 v[28:31], v[156:159], v[188:191], v[28:31]
	v_mfma_f32_16x16x32_f16 v[32:35], v[160:163], v[188:191], v[32:35]
	s_waitcnt lgkmcnt(0)
	s_barrier
	v_mfma_f32_16x16x32_f16 v[36:39], v[148:151], v[192:195], v[36:39]
	v_mfma_f32_16x16x32_f16 v[40:43], v[152:155], v[192:195], v[40:43]
	v_mfma_f32_16x16x32_f16 v[44:47], v[156:159], v[192:195], v[44:47]
	v_mfma_f32_16x16x32_f16 v[48:51], v[160:163], v[192:195], v[48:51]
	v_mfma_f32_16x16x32_f16 v[52:55], v[148:151], v[196:199], v[52:55]
	v_mfma_f32_16x16x32_f16 v[56:59], v[152:155], v[196:199], v[56:59]
	v_mfma_f32_16x16x32_f16 v[60:63], v[156:159], v[196:199], v[60:63]
	v_mfma_f32_16x16x32_f16 v[64:67], v[160:163], v[196:199], v[64:67]
	s_sub_u32 s77, s50, 0x1000
	s_lshr_b32 s77, s77, 12
	s_add_u32 s77, s77, 1
	s_cmp_lt_u32 s50, 0x1000
	s_cselect_b32 s77, 0, s77
	s_mul_i32 s77, s77, 0x6000
	s_add_u32 s68, s26, s77
	s_addc_u32 s69, s27, 0
	s_add_u32 s68, s68, 0x2000
	s_addc_u32 s69, s69, 0
	s_lshl_b32 s82, s50, 11
	s_add_u32 s80, s42, s82
	s_addc_u32 s81, s43, 0
	s_lshl_b32 s82, s37, 1
	s_add_u32 s80, s80, s82
	s_addc_u32 s81, s81, 0
	v_and_b32_e32 v172, 15, v200
	v_bfe_u32 v173, v200, 4, 2
	v_bfe_u32 v174, v200, 6, 1
	v_bfe_u32 v175, v200, 7, 2
	v_lshlrev_b32_e32 v176, 6, v174
	v_lshl_or_b32 v176, v173, 2, v176
	v_lshl_or_b32 v175, v175, 6, v172
	v_lshlrev_b32_e32 v175, 11, v175
	v_lshl_add_u32 v177, v176, 1, v175
	v_lshlrev_b32_e32 v178, 1, v175
	v_lshl_add_u32 v178, v176, 2, v178
	s_cmp_lt_u32 s50, 0x1000
	s_cselect_b32 s77, 0, 8
	s_load_dwordx2 s[28:29], s[22:23], s77
	s_sub_u32 s77, s50, 0x1000
	s_cselect_b32 s77, s50, s77
	s_lshl_b32 s77, s77, 12
	s_lshl_b32 s82, s37, 2
	s_add_u32 s77, s77, s82
	s_waitcnt lgkmcnt(0)
	s_add_u32 s28, s28, s77
	s_addc_u32 s29, s29, 0
	v_add_u32_e32 v176, s37, v176
	v_lshlrev_b32_e32 v176, 2, v176
	global_load_dwordx4 v[132:135], v176, s[68:69]
	global_load_dwordx4 v[136:139], v176, s[68:69] offset:64
	global_load_dwordx4 v[140:143], v176, s[68:69] offset:128
	global_load_dwordx4 v[144:147], v176, s[68:69] offset:192
	v_and_b32_e32 v172, 1, v173
	v_mul_u32_u24_e32 v172, 24, v172
	v_add_u32_e32 v177, v177, v172
	global_load_dwordx4 v[184:187], v178, s[28:29]
	global_load_dwordx4 v[188:191], v178, s[28:29] offset:64
	global_load_dwordx4 v[192:195], v178, s[28:29] offset:128
	global_load_dwordx4 v[196:199], v178, s[28:29] offset:192
	v_add_u32_e32 v178, 0x10000, v178
	global_load_dwordx4 v[68:71], v178, s[28:29]
	global_load_dwordx4 v[72:75], v178, s[28:29] offset:64
	global_load_dwordx4 v[76:79], v178, s[28:29] offset:128
	global_load_dwordx4 v[80:83], v178, s[28:29] offset:192
	s_waitcnt vmcnt(6)
	v_pk_mul_f32 v[184:185], v[184:185], s[84:85] op_sel_hi:[1,0]
	v_pk_mul_f32 v[186:187], v[186:187], s[84:85] op_sel_hi:[1,0]
	v_pk_fma_f32 v[4:5], v[4:5], v[132:133], v[184:185]
	v_pk_fma_f32 v[6:7], v[6:7], v[134:135], v[186:187]
	v_cvt_pk_f16_f32 v172, v4, v5
	v_cvt_pk_f16_f32 v173, v6, v7
	v_pk_mul_f32 v[188:189], v[188:189], s[84:85] op_sel_hi:[1,0]
	v_pk_mul_f32 v[190:191], v[190:191], s[84:85] op_sel_hi:[1,0]
	v_pk_fma_f32 v[8:9], v[8:9], v[136:137], v[188:189]
	v_pk_fma_f32 v[10:11], v[10:11], v[138:139], v[190:191]
	v_cvt_pk_f16_f32 v174, v8, v9
	v_cvt_pk_f16_f32 v175, v10, v11
	s_nop 1
	v_permlane16_swap_b32_e32 v172, v174
	v_permlane16_swap_b32_e32 v173, v175
	global_store_dwordx4 v177, v[172:175], s[80:81]
	s_waitcnt vmcnt(5)
	v_pk_mul_f32 v[192:193], v[192:193], s[84:85] op_sel_hi:[1,0]
	v_pk_mul_f32 v[194:195], v[194:195], s[84:85] op_sel_hi:[1,0]
	v_pk_fma_f32 v[12:13], v[12:13], v[140:141], v[192:193]
	v_pk_fma_f32 v[14:15], v[14:15], v[142:143], v[194:195]
	v_cvt_pk_f16_f32 v228, v12, v13
	v_cvt_pk_f16_f32 v229, v14, v15
	v_pk_mul_f32 v[196:197], v[196:197], s[84:85] op_sel_hi:[1,0]
	v_pk_mul_f32 v[198:199], v[198:199], s[84:85] op_sel_hi:[1,0]
	v_pk_fma_f32 v[16:17], v[16:17], v[144:145], v[196:197]
	v_pk_fma_f32 v[18:19], v[18:19], v[146:147], v[198:199]
	v_cvt_pk_f16_f32 v230, v16, v17
	v_cvt_pk_f16_f32 v231, v18, v19
	s_nop 1
	v_permlane16_swap_b32_e32 v228, v230
	v_permlane16_swap_b32_e32 v229, v231
	global_store_dwordx4 v177, v[228:231], s[80:81] offset:64
	v_add_u32_e32 v177, 0x8000, v177
	v_add_u32_e32 v178, 0x10000, v178
	global_load_dwordx4 v[184:187], v178, s[28:29]
	global_load_dwordx4 v[188:191], v178, s[28:29] offset:64
	global_load_dwordx4 v[192:195], v178, s[28:29] offset:128
	global_load_dwordx4 v[196:199], v178, s[28:29] offset:192
	s_waitcnt vmcnt(8)
	v_pk_mul_f32 v[68:69], v[68:69], s[84:85] op_sel_hi:[1,0]
	v_pk_mul_f32 v[70:71], v[70:71], s[84:85] op_sel_hi:[1,0]
	v_pk_fma_f32 v[20:21], v[20:21], v[132:133], v[68:69]
	v_pk_fma_f32 v[22:23], v[22:23], v[134:135], v[70:71]
	v_cvt_pk_f16_f32 v172, v20, v21
	v_cvt_pk_f16_f32 v173, v22, v23
	v_pk_mul_f32 v[72:73], v[72:73], s[84:85] op_sel_hi:[1,0]
	v_pk_mul_f32 v[74:75], v[74:75], s[84:85] op_sel_hi:[1,0]
	v_pk_fma_f32 v[24:25], v[24:25], v[136:137], v[72:73]
	v_pk_fma_f32 v[26:27], v[26:27], v[138:139], v[74:75]
	v_cvt_pk_f16_f32 v174, v24, v25
	v_cvt_pk_f16_f32 v175, v26, v27
	s_nop 1
	v_permlane16_swap_b32_e32 v172, v174
	v_permlane16_swap_b32_e32 v173, v175
	global_store_dwordx4 v177, v[172:175], s[80:81]
	s_waitcnt vmcnt(7)
	v_pk_mul_f32 v[76:77], v[76:77], s[84:85] op_sel_hi:[1,0]
	v_pk_mul_f32 v[78:79], v[78:79], s[84:85] op_sel_hi:[1,0]
	v_pk_fma_f32 v[28:29], v[28:29], v[140:141], v[76:77]
	v_pk_fma_f32 v[30:31], v[30:31], v[142:143], v[78:79]
	v_cvt_pk_f16_f32 v228, v28, v29
	v_cvt_pk_f16_f32 v229, v30, v31
	v_pk_mul_f32 v[80:81], v[80:81], s[84:85] op_sel_hi:[1,0]
	v_pk_mul_f32 v[82:83], v[82:83], s[84:85] op_sel_hi:[1,0]
	v_pk_fma_f32 v[32:33], v[32:33], v[144:145], v[80:81]
	v_pk_fma_f32 v[34:35], v[34:35], v[146:147], v[82:83]
	v_cvt_pk_f16_f32 v230, v32, v33
	v_cvt_pk_f16_f32 v231, v34, v35
	s_nop 1
	v_permlane16_swap_b32_e32 v228, v230
	v_permlane16_swap_b32_e32 v229, v231
	global_store_dwordx4 v177, v[228:231], s[80:81] offset:64
	v_add_u32_e32 v177, 0x8000, v177
	v_add_u32_e32 v178, 0x10000, v178
	global_load_dwordx4 v[68:71], v178, s[28:29]
	global_load_dwordx4 v[72:75], v178, s[28:29] offset:64
	global_load_dwordx4 v[76:79], v178, s[28:29] offset:128
	global_load_dwordx4 v[80:83], v178, s[28:29] offset:192
	s_waitcnt vmcnt(8)
	v_pk_mul_f32 v[184:185], v[184:185], s[84:85] op_sel_hi:[1,0]
	v_pk_mul_f32 v[186:187], v[186:187], s[84:85] op_sel_hi:[1,0]
	v_pk_fma_f32 v[36:37], v[36:37], v[132:133], v[184:185]
	v_pk_fma_f32 v[38:39], v[38:39], v[134:135], v[186:187]
	v_cvt_pk_f16_f32 v172, v36, v37
	v_cvt_pk_f16_f32 v173, v38, v39
	v_pk_mul_f32 v[188:189], v[188:189], s[84:85] op_sel_hi:[1,0]
	v_pk_mul_f32 v[190:191], v[190:191], s[84:85] op_sel_hi:[1,0]
	v_pk_fma_f32 v[40:41], v[40:41], v[136:137], v[188:189]
	v_pk_fma_f32 v[42:43], v[42:43], v[138:139], v[190:191]
	v_cvt_pk_f16_f32 v174, v40, v41
	v_cvt_pk_f16_f32 v175, v42, v43
	s_nop 1
	v_permlane16_swap_b32_e32 v172, v174
	v_permlane16_swap_b32_e32 v173, v175
	global_store_dwordx4 v177, v[172:175], s[80:81]
	s_waitcnt vmcnt(7)
	v_pk_mul_f32 v[192:193], v[192:193], s[84:85] op_sel_hi:[1,0]
	v_pk_mul_f32 v[194:195], v[194:195], s[84:85] op_sel_hi:[1,0]
	v_pk_fma_f32 v[44:45], v[44:45], v[140:141], v[192:193]
	v_pk_fma_f32 v[46:47], v[46:47], v[142:143], v[194:195]
	v_cvt_pk_f16_f32 v228, v44, v45
	v_cvt_pk_f16_f32 v229, v46, v47
	v_pk_mul_f32 v[196:197], v[196:197], s[84:85] op_sel_hi:[1,0]
	v_pk_mul_f32 v[198:199], v[198:199], s[84:85] op_sel_hi:[1,0]
	v_pk_fma_f32 v[48:49], v[48:49], v[144:145], v[196:197]
	v_pk_fma_f32 v[50:51], v[50:51], v[146:147], v[198:199]
	v_cvt_pk_f16_f32 v230, v48, v49
	v_cvt_pk_f16_f32 v231, v50, v51
	s_nop 1
	v_permlane16_swap_b32_e32 v228, v230
	v_permlane16_swap_b32_e32 v229, v231
	global_store_dwordx4 v177, v[228:231], s[80:81] offset:64
	v_add_u32_e32 v177, 0x8000, v177
	s_waitcnt vmcnt(4)
	v_pk_mul_f32 v[68:69], v[68:69], s[84:85] op_sel_hi:[1,0]
	v_pk_mul_f32 v[70:71], v[70:71], s[84:85] op_sel_hi:[1,0]
	v_pk_fma_f32 v[52:53], v[52:53], v[132:133], v[68:69]
	v_pk_fma_f32 v[54:55], v[54:55], v[134:135], v[70:71]
	v_cvt_pk_f16_f32 v172, v52, v53
	v_cvt_pk_f16_f32 v173, v54, v55
	v_pk_mul_f32 v[72:73], v[72:73], s[84:85] op_sel_hi:[1,0]
	v_pk_mul_f32 v[74:75], v[74:75], s[84:85] op_sel_hi:[1,0]
	v_pk_fma_f32 v[56:57], v[56:57], v[136:137], v[72:73]
	v_pk_fma_f32 v[58:59], v[58:59], v[138:139], v[74:75]
	v_cvt_pk_f16_f32 v174, v56, v57
	v_cvt_pk_f16_f32 v175, v58, v59
	s_nop 1
	v_permlane16_swap_b32_e32 v172, v174
	v_permlane16_swap_b32_e32 v173, v175
	global_store_dwordx4 v177, v[172:175], s[80:81]
	s_waitcnt vmcnt(3)
	v_pk_mul_f32 v[76:77], v[76:77], s[84:85] op_sel_hi:[1,0]
	v_pk_mul_f32 v[78:79], v[78:79], s[84:85] op_sel_hi:[1,0]
	v_pk_fma_f32 v[60:61], v[60:61], v[140:141], v[76:77]
	v_pk_fma_f32 v[62:63], v[62:63], v[142:143], v[78:79]
	v_cvt_pk_f16_f32 v228, v60, v61
	v_cvt_pk_f16_f32 v229, v62, v63
	v_pk_mul_f32 v[80:81], v[80:81], s[84:85] op_sel_hi:[1,0]
	v_pk_mul_f32 v[82:83], v[82:83], s[84:85] op_sel_hi:[1,0]
	v_pk_fma_f32 v[64:65], v[64:65], v[144:145], v[80:81]
	v_pk_fma_f32 v[66:67], v[66:67], v[146:147], v[82:83]
	v_cvt_pk_f16_f32 v230, v64, v65
	v_cvt_pk_f16_f32 v231, v66, v67
	s_nop 1
	v_permlane16_swap_b32_e32 v228, v230
	v_permlane16_swap_b32_e32 v229, v231
	global_store_dwordx4 v177, v[228:231], s[80:81] offset:64
	s_nop 1
	s_addk_i32 s35, 0x1000
	s_add_i32 s34, s34, 4
	s_add_i32 s28, s36, 32
	s_cmp_gt_u32 s36, 31
	s_mov_b32 s36, s28
	s_cbranch_scc1 .LBB0_1289
	s_branch .LBB0_1270
